# diff-attn k-loop rewritten: rotated MFMA-phase/softmax-phase with 12-slot LDS fragment ring, wave halves offset by one softmax phase
# speedup vs baseline: 1.0230x; 1.0230x over previous
; #define LAS __attribute__((address_space(3)))
; #define GAS __attribute__((address_space(1)))
; #define ATT_LOADK(kt) do { const int k0_ = ATT_KEY0(kt); \
;         _Pragma("unroll") for (int p = 0; p < KPT; ++p) { const int c = tid + 512 * p; if (c < KCH) kr[p] = *(const GAS u32x4*)((const GAS char*)(Kb + (size_t)k0_ * DQK) + (unsigned)(c * 16)); } } while (0)
; #define ATT_LOADV(kt) do { const int k0_ = ATT_KEY0(kt); \
;         _Pragma("unroll") for (int p = 0; p < VPT; ++p) vr[p] = *(const GAS u32x4*)((const GAS char*)(Vb + k0_) + lvo[p]); } while (0)
; #define ATT_STOREK(buf) do { \
;         _Pragma("unroll") for (int p = 0; p < KPT; ++p) { const int c = tid + 512 * p; if (c < KCH) *(LAS u32x4*)(lds + (buf) * KBYTES + (c / CPR) * KS + (c % CPR) * 16) = kr[p]; } } while (0)
; template <int DQK, int DV, int NAT, int VSHIFT, int COMB> ...
;     ...
;         const int pos_q = qb * 256 + w * 32 + n;
;         const int qr = (qb - 1) * 4 + (w >> 1), qrs = min(max(qr - 4, 0), 120);
;         int lq_ = lane; asm volatile("" : "+v"(lq_));
;         const bf16_t* qp = Q + ((size_t)bv * TPB + qb * 256 + w * 32 + (lq_ & 31)) * DQK + (lq_ >> 5) * 8;
;         bf16x8 qg[DQK / 16];
; #pragma unroll
;         for (int ks = 0; ks < DQK / 16; ++ks) qg[ks] = *(const GAS bf16x8*)(qp + ks * 16);
;         LAS unsigned char* qs = lds + QOFF + w * QW + lane * 16;
;         f32x16 o[DV / 32];
; #pragma unroll
;         for (int dt = 0; dt < DV / 32; ++dt)
; #pragma unroll
;             for (int i = 0; i < 16; ++i) o[dt][i] = 0.f;
;         float l_run = 0.f;
;         f32x16 negm;
; #pragma unroll
;         for (int i = 0; i < 16; ++i) negm[i] = 0.f;
;     ...
;         __syncthreads();
;         if (NAT) { for (int i = tid; i < 465; i += 512) rpb_s[i] = rpb[vh * 465 + i]; }
; #pragma unroll
;         for (int ks = 0; ks < DQK / 16; ++ks) { if (!QREG) *(LAS bf16x8*)(qs + ks * 1024) = qg[ks]; }
;         if (K128) { ATT_DMAK(0, 0); ATT_DMAV(0, 0); ATT_DMAK(1, 1); ATT_DMAV(1, 1); ATT_DMAK(2, 2); asm volatile("s_waitcnt vmcnt(0)" ::: "memory"); }
;         else if (DMA) { ATT_DMAK(0, 0); ATT_DMAV(0, 0); ATT_DMAK(1, 1); asm volatile("s_waitcnt vmcnt(0)" ::: "memory"); }
;         else { ATT_LOADK(0); ATT_STOREK(0); ATT_LOADV(0); ATT_STOREV(0); ATT_LOADK(1); ATT_STOREK(1); }
;         __syncthreads();
;         f32x16 sA0, sA1, sB0, sB1;
;         ATT_QK(sA0, sA1, 0);
;         __syncthreads();
.LBB0_706:
	s_xor_b64 s[20:21], s[0:1], -1
	s_or_b32 s0, s42, s31
	s_xor_b64 s[24:25], s[6:7], -1
	s_and_b32 s2, s0, 15
	s_bfe_u32 s39, s0, 0x30001
	s_mul_i32 s5, s0, 0x2100
	s_mul_hi_i32 s1, s0, 0x2100
	s_add_u32 s5, s36, s5
	v_mov_b32_e32 v4, v210
	s_addc_u32 s1, s37, s1
	v_mov_b32_e32 v3, s1
	v_and_or_b32 v2, v4, 31, s5
	v_readlane_b32 s8, v253, 40
	v_lshlrev_b64 v[2:3], 7, v[2:3]
	v_readlane_b32 s9, v253, 41
	s_mul_hi_i32 s6, s0, 0x108000
	s_mul_i32 s0, s0, 0x108000
	v_lshl_add_u64 v[2:3], s[8:9], 0, v[2:3]
	v_ashrrev_i32_e32 v4, 2, v4
	v_readlane_b32 s8, v253, 42
	v_and_b32_e32 v4, -8, v4
	v_readlane_b32 s9, v253, 43
	s_add_u32 s0, s8, s0
	v_ashrrev_i32_e32 v5, 31, v4
	s_addc_u32 s1, s9, s6
	s_mul_i32 s5, s39, 0x840000
	v_lshl_add_u64 v[2:3], v[4:5], 1, v[2:3]
	s_add_u32 s6, s34, s5
	s_mov_b32 m0, s28
	global_load_dwordx4 v[146:149], v[2:3], off
	global_load_dwordx4 v[150:153], v[2:3], off offset:32
	global_load_dwordx4 v[154:157], v[2:3], off offset:64
	global_load_dwordx4 v[158:161], v[2:3], off offset:96
	s_addc_u32 s7, s35, 0
	v_lshl_add_u64 v[2:3], s[0:1], 0, v[0:1]
	s_barrier
	global_load_lds_dwordx4 v[2:3], off
	v_lshl_add_u64 v[4:5], s[6:7], 0, v[176:177]
	s_add_i32 m0, s28, 0x8000
	v_lshl_add_u64 v[6:7], s[6:7], 0, v[178:179]
	global_load_lds_dwordx4 v[4:5], off
	s_add_i32 m0, s28, 0xa000
	v_lshl_add_u64 v[8:9], v[2:3], 0, s[96:97]
	global_load_lds_dwordx4 v[6:7], off
	s_add_i32 m0, s28, 0x2000
	v_lshl_add_u64 v[4:5], v[4:5], 0, s[74:75]
	global_load_lds_dwordx4 v[8:9], off
	s_add_i32 m0, s28, 0xc000
	v_lshl_add_u64 v[2:3], v[2:3], 0, s[82:83]
	global_load_lds_dwordx4 v[4:5], off
	v_lshl_add_u64 v[4:5], v[6:7], 0, s[74:75]
	s_add_i32 m0, s28, 0xe000
	v_add_u32_e32 v6, v211, v212
	global_load_lds_dwordx4 v[4:5], off
	s_add_i32 m0, s28, 0x4000
	v_add_u32_e32 v14, v211, v213
	global_load_lds_dwordx4 v[2:3], off
	v_add_u32_e32 v22, v211, v214
	v_add_u32_e32 v30, v211, v215
	s_waitcnt vmcnt(0)
	s_waitcnt vmcnt(0) lgkmcnt(0)
	s_barrier
	ds_read_b128 v[2:5], v6
	ds_read_b128 v[6:9], v6 offset:4096
	ds_read_b128 v[10:13], v14
	ds_read_b128 v[14:17], v14 offset:4096
	ds_read_b128 v[18:21], v22
	ds_read_b128 v[22:25], v22 offset:4096
	ds_read_b128 v[26:29], v30
	ds_read_b128 v[30:33], v30 offset:4096
	s_mov_b32 s41, 2
	s_mov_b32 s40, 0x8000
	s_waitcnt lgkmcnt(7)
	v_mfma_f32_32x32x16_bf16 v[98:113], v[2:5], v[146:149], 0
	s_mov_b32 s5, s4
	s_mov_b32 s6, s4
	s_mov_b32 s7, s4
	s_mov_b32 s8, s4
	s_mov_b32 s9, s4
	s_mov_b32 s10, s4
	s_mov_b32 s11, s4
	s_waitcnt lgkmcnt(6)
	v_mfma_f32_32x32x16_bf16 v[82:97], v[6:9], v[146:149], 0
	s_mov_b32 s12, s4
	s_mov_b32 s13, s4
	s_mov_b32 s14, s4
	s_mov_b32 s15, s4
	s_mov_b32 s16, s4
	s_mov_b32 s17, s4
	s_mov_b32 s18, s4
	s_waitcnt lgkmcnt(5)
	v_mfma_f32_32x32x16_bf16 v[98:113], v[10:13], v[150:153], v[98:113]
	s_mov_b32 s19, s4
	s_waitcnt lgkmcnt(4)
	v_mfma_f32_32x32x16_bf16 v[82:97], v[14:17], v[150:153], v[82:97]
	v_mov_b64_e32 v[2:3], s[4:5]
	v_mov_b64_e32 v[4:5], s[6:7]
	v_mov_b64_e32 v[6:7], s[8:9]
	v_mov_b64_e32 v[8:9], s[10:11]
	v_mov_b64_e32 v[10:11], s[12:13]
	v_mov_b64_e32 v[12:13], s[14:15]
	v_mov_b64_e32 v[14:15], s[16:17]
	s_waitcnt lgkmcnt(3)
	v_mfma_f32_32x32x16_bf16 v[98:113], v[18:21], v[154:157], v[98:113]
	v_mov_b64_e32 v[16:17], s[18:19]
	s_waitcnt lgkmcnt(2)
	v_mfma_f32_32x32x16_bf16 v[82:97], v[22:25], v[154:157], v[82:97]
	s_waitcnt lgkmcnt(1)
	v_mfma_f32_32x32x16_bf16 v[98:113], v[26:29], v[158:161], v[98:113]
	s_waitcnt lgkmcnt(0)
	v_mfma_f32_32x32x16_bf16 v[82:97], v[30:33], v[158:161], v[82:97]
	s_add_i32 s5, s31, s42
	s_bfe_u32 s6, s5, 0x30001
	v_mov_b64_e32 v[64:65], v[16:17]
	v_mov_b64_e32 v[48:49], v[16:17]
	v_mov_b64_e32 v[32:33], v[16:17]
	v_mov_b64_e32 v[80:81], v[16:17]
	v_mad_u64_u32 v[190:191], s[0:1], s6, v207, v[186:187]
	v_mad_u64_u32 v[192:193], s[0:1], s6, v207, v[188:189]
	v_mad_i64_i32 v[194:195], s[0:1], s5, v208, v[184:185]
	v_mov_b32_e32 v197, 0
	s_mov_b32 s5, 0
	v_mov_b64_e32 v[62:63], v[14:15]
	v_mov_b64_e32 v[60:61], v[12:13]
	v_mov_b64_e32 v[58:59], v[10:11]
	v_mov_b64_e32 v[56:57], v[8:9]
	v_mov_b64_e32 v[54:55], v[6:7]
	v_mov_b64_e32 v[52:53], v[4:5]
	v_mov_b64_e32 v[50:51], v[2:3]
	v_mov_b64_e32 v[46:47], v[14:15]
	v_mov_b64_e32 v[44:45], v[12:13]
	v_mov_b64_e32 v[42:43], v[10:11]
	v_mov_b64_e32 v[40:41], v[8:9]
	v_mov_b64_e32 v[38:39], v[6:7]
	v_mov_b64_e32 v[36:37], v[4:5]
	v_mov_b64_e32 v[34:35], v[2:3]
	v_mov_b64_e32 v[30:31], v[14:15]
	v_mov_b64_e32 v[28:29], v[12:13]
	v_mov_b64_e32 v[26:27], v[10:11]
	v_mov_b64_e32 v[24:25], v[8:9]
	v_mov_b64_e32 v[22:23], v[6:7]
	v_mov_b64_e32 v[20:21], v[4:5]
	v_mov_b64_e32 v[18:19], v[2:3]
	v_mov_b64_e32 v[78:79], v[14:15]
	v_mov_b64_e32 v[76:77], v[12:13]
	v_mov_b64_e32 v[74:75], v[10:11]
	v_mov_b64_e32 v[72:73], v[8:9]
	v_mov_b64_e32 v[70:71], v[6:7]
	v_mov_b64_e32 v[68:69], v[4:5]
	v_mov_b64_e32 v[66:67], v[2:3]
	s_barrier
	v_readlane_b32 s0, v252, 7
	s_cmpk_lt_u32 s0, 0x100
	s_cbranch_scc0 .Ldpre_skip
	s_mov_b64 s[6:7], -1
	s_mov_b64 s[8:9], 0
.Ldv_pre_top:
	v_exp_f32_e32 v130, v98
	v_exp_f32_e32 v222, v82
	v_exp_f32_e32 v131, v99
	v_exp_f32_e32 v223, v83
	v_exp_f32_e32 v132, v100
	v_add_f32_e32 v196, v130, v131
	v_exp_f32_e32 v224, v84
	v_add_f32_e32 v198, v222, v223
	v_exp_f32_e32 v133, v101
	v_add_f32_e32 v196, v132, v196
	v_exp_f32_e32 v225, v85
	v_add_f32_e32 v198, v224, v198
	v_exp_f32_e32 v134, v102
	v_add_f32_e32 v196, v133, v196
	v_exp_f32_e32 v226, v86
	v_add_f32_e32 v198, v225, v198
	v_exp_f32_e32 v135, v103
	v_add_f32_e32 v196, v134, v196
	v_exp_f32_e32 v227, v87
	v_add_f32_e32 v198, v226, v198
	v_exp_f32_e32 v136, v104
	v_add_f32_e32 v196, v135, v196
	v_exp_f32_e32 v228, v88
	v_add_f32_e32 v198, v227, v198
	v_exp_f32_e32 v137, v105
	v_add_f32_e32 v196, v136, v196
	v_exp_f32_e32 v229, v89
	v_add_f32_e32 v198, v228, v198
	v_exp_f32_e32 v138, v106
	v_add_f32_e32 v196, v137, v196
	v_exp_f32_e32 v230, v90
	v_add_f32_e32 v198, v229, v198
	v_exp_f32_e32 v139, v107
	v_add_f32_e32 v196, v138, v196
	v_exp_f32_e32 v231, v91
	v_add_f32_e32 v198, v230, v198
	v_exp_f32_e32 v140, v108
	v_add_f32_e32 v196, v139, v196
	v_exp_f32_e32 v232, v92
	v_add_f32_e32 v198, v231, v198
	v_exp_f32_e32 v141, v109
	v_add_f32_e32 v196, v140, v196
	v_exp_f32_e32 v233, v93
	v_add_f32_e32 v198, v232, v198
	v_exp_f32_e32 v142, v110
	v_add_f32_e32 v196, v141, v196
	v_exp_f32_e32 v234, v94
	v_add_f32_e32 v198, v233, v198
	v_exp_f32_e32 v143, v111
	v_add_f32_e32 v196, v142, v196
	v_exp_f32_e32 v235, v95
	v_add_f32_e32 v198, v234, v198
	v_exp_f32_e32 v144, v112
	v_add_f32_e32 v196, v143, v196
	v_exp_f32_e32 v236, v96
	v_add_f32_e32 v198, v235, v198
	v_exp_f32_e32 v145, v113
	v_add_f32_e32 v196, v144, v196
	v_exp_f32_e32 v237, v97
	v_add_f32_e32 v198, v236, v198
	v_add_f32_e32 v196, v145, v196
	v_add_f32_e32 v198, v237, v198
	v_add_f32_e32 v199, v196, v198
	s_nop 0
	v_cmp_ngt_f32_e32 vcc, s72, v199
	s_nop 1
	s_or_b64 vcc, vcc, s[6:7]
	s_andn2_b64 vcc, vcc, s[8:9]
	s_cbranch_vccz .Ldv_pre_fast
	v_max3_f32 v221, v98, v99, v100
	v_max3_f32 v221, v221, v101, v102
	v_max3_f32 v221, v221, v103, v104
	v_max3_f32 v221, v221, v105, v106
	v_max3_f32 v221, v221, v107, v108
	v_max3_f32 v221, v221, v109, v110
	v_max3_f32 v221, v221, v111, v112
	v_max3_f32 v221, v221, v113, v82
	v_max3_f32 v221, v221, v83, v84
	v_max3_f32 v221, v221, v85, v86
	v_max3_f32 v221, v221, v87, v88
	v_max3_f32 v221, v221, v89, v90
	v_max3_f32 v221, v221, v91, v92
	v_max3_f32 v221, v221, v93, v94
	v_max3_f32 v221, v221, v95, v96
	v_max_f32_e32 v221, v221, v97
	ds_bpermute_b32 v162, v173, v221
	s_waitcnt lgkmcnt(0)
	v_max_f32_e32 v221, v221, v162
	s_and_b64 vcc, exec, s[6:7]
	s_cbranch_vccnz .Ldv_pre_anchor
	v_max_f32_e32 v221, 0, v221
	v_exp_f32_e64 v163, -v221
	s_nop 7
	s_nop 7
	v_mul_f32_e32 v197, v197, v163
	v_mul_f32_e32 v2, v2, v163
	v_mul_f32_e32 v3, v3, v163
	v_mul_f32_e32 v4, v4, v163
	v_mul_f32_e32 v5, v5, v163
	v_mul_f32_e32 v6, v6, v163
	v_mul_f32_e32 v7, v7, v163
	v_mul_f32_e32 v8, v8, v163
	v_mul_f32_e32 v9, v9, v163
	v_mul_f32_e32 v10, v10, v163
	v_mul_f32_e32 v11, v11, v163
	v_mul_f32_e32 v12, v12, v163
	v_mul_f32_e32 v13, v13, v163
	v_mul_f32_e32 v14, v14, v163
	v_mul_f32_e32 v15, v15, v163
	v_mul_f32_e32 v16, v16, v163
	v_mul_f32_e32 v17, v17, v163
	v_mul_f32_e32 v50, v50, v163
	v_mul_f32_e32 v51, v51, v163
	v_mul_f32_e32 v52, v52, v163
	v_mul_f32_e32 v53, v53, v163
	v_mul_f32_e32 v54, v54, v163
	v_mul_f32_e32 v55, v55, v163
	v_mul_f32_e32 v56, v56, v163
	v_mul_f32_e32 v57, v57, v163
	v_mul_f32_e32 v58, v58, v163
	v_mul_f32_e32 v59, v59, v163
	v_mul_f32_e32 v60, v60, v163
	v_mul_f32_e32 v61, v61, v163
	v_mul_f32_e32 v62, v62, v163
	v_mul_f32_e32 v63, v63, v163
	v_mul_f32_e32 v64, v64, v163
	v_mul_f32_e32 v65, v65, v163
	v_mul_f32_e32 v34, v34, v163
	v_mul_f32_e32 v35, v35, v163
	v_mul_f32_e32 v36, v36, v163
	v_mul_f32_e32 v37, v37, v163
	v_mul_f32_e32 v38, v38, v163
	v_mul_f32_e32 v39, v39, v163
	v_mul_f32_e32 v40, v40, v163
	v_mul_f32_e32 v41, v41, v163
	v_mul_f32_e32 v42, v42, v163
	v_mul_f32_e32 v43, v43, v163
	v_mul_f32_e32 v44, v44, v163
	v_mul_f32_e32 v45, v45, v163
	v_mul_f32_e32 v46, v46, v163
	v_mul_f32_e32 v47, v47, v163
	v_mul_f32_e32 v48, v48, v163
	v_mul_f32_e32 v49, v49, v163
	v_mul_f32_e32 v18, v18, v163
	v_mul_f32_e32 v19, v19, v163
	v_mul_f32_e32 v20, v20, v163
	v_mul_f32_e32 v21, v21, v163
	v_mul_f32_e32 v22, v22, v163
	v_mul_f32_e32 v23, v23, v163
	v_mul_f32_e32 v24, v24, v163
	v_mul_f32_e32 v25, v25, v163
	v_mul_f32_e32 v26, v26, v163
	v_mul_f32_e32 v27, v27, v163
	v_mul_f32_e32 v28, v28, v163
	v_mul_f32_e32 v29, v29, v163
	v_mul_f32_e32 v30, v30, v163
	v_mul_f32_e32 v31, v31, v163
	v_mul_f32_e32 v32, v32, v163
	v_mul_f32_e32 v33, v33, v163
.Ldv_pre_anchor:
	v_sub_f32_e32 v98, v98, v221
	v_sub_f32_e32 v99, v99, v221
	v_sub_f32_e32 v100, v100, v221
	v_sub_f32_e32 v101, v101, v221
	v_sub_f32_e32 v102, v102, v221
	v_sub_f32_e32 v103, v103, v221
	v_sub_f32_e32 v104, v104, v221
	v_sub_f32_e32 v105, v105, v221
	v_sub_f32_e32 v106, v106, v221
	v_sub_f32_e32 v107, v107, v221
	v_sub_f32_e32 v108, v108, v221
	v_sub_f32_e32 v109, v109, v221
	v_sub_f32_e32 v110, v110, v221
	v_sub_f32_e32 v111, v111, v221
	v_sub_f32_e32 v112, v112, v221
	v_sub_f32_e32 v113, v113, v221
	v_sub_f32_e32 v82, v82, v221
	v_sub_f32_e32 v83, v83, v221
	v_sub_f32_e32 v84, v84, v221
	v_sub_f32_e32 v85, v85, v221
	v_sub_f32_e32 v86, v86, v221
	v_sub_f32_e32 v87, v87, v221
	v_sub_f32_e32 v88, v88, v221
	v_sub_f32_e32 v89, v89, v221
	v_sub_f32_e32 v90, v90, v221
	v_sub_f32_e32 v91, v91, v221
	v_sub_f32_e32 v92, v92, v221
	v_sub_f32_e32 v93, v93, v221
	v_sub_f32_e32 v94, v94, v221
	v_sub_f32_e32 v95, v95, v221
	v_sub_f32_e32 v96, v96, v221
	v_sub_f32_e32 v97, v97, v221
	v_sub_f32_e32 v66, v66, v221
	v_sub_f32_e32 v67, v67, v221
	v_sub_f32_e32 v68, v68, v221
	v_sub_f32_e32 v69, v69, v221
	v_sub_f32_e32 v70, v70, v221
	v_sub_f32_e32 v71, v71, v221
	v_sub_f32_e32 v72, v72, v221
	v_sub_f32_e32 v73, v73, v221
	v_sub_f32_e32 v74, v74, v221
	v_sub_f32_e32 v75, v75, v221
	v_sub_f32_e32 v76, v76, v221
	v_sub_f32_e32 v77, v77, v221
	v_sub_f32_e32 v78, v78, v221
	v_sub_f32_e32 v79, v79, v221
	v_sub_f32_e32 v80, v80, v221
	v_sub_f32_e32 v81, v81, v221
	s_mov_b64 s[8:9], -1
	s_branch .Ldv_pre_top
.Ldv_pre_fast:
	v_cvt_pk_bf16_f32 v114, v130, v131
	v_cvt_pk_bf16_f32 v115, v132, v133
	v_cvt_pk_bf16_f32 v116, v134, v135
	v_cvt_pk_bf16_f32 v117, v136, v137
	v_cvt_pk_bf16_f32 v118, v138, v139
	v_cvt_pk_bf16_f32 v119, v140, v141
	v_cvt_pk_bf16_f32 v120, v142, v143
	v_cvt_pk_bf16_f32 v121, v144, v145
	v_cvt_pk_bf16_f32 v122, v222, v223
	v_cvt_pk_bf16_f32 v123, v224, v225
	v_cvt_pk_bf16_f32 v124, v226, v227
	v_cvt_pk_bf16_f32 v125, v228, v229
	v_cvt_pk_bf16_f32 v126, v230, v231
	v_cvt_pk_bf16_f32 v127, v232, v233
	v_cvt_pk_bf16_f32 v128, v234, v235
	v_cvt_pk_bf16_f32 v129, v236, v237
	v_add_f32_e32 v197, v197, v199
.Ldpre_skip:
.LBB0_707:
	s_add_i32 s10, s41, 2
	s_add_i32 s12, s41, -1
	s_and_b32 s11, s12, 3
	s_add_i32 s0, s41, 1
	s_cmp_ge_u32 s0, s30
	s_cbranch_scc1 .Ldk_skip1
	s_add_i32 s0, s5, 0x6000
	s_and_b32 s0, s0, 0x6000
	s_add_i32 m0, s28, s0
	v_lshl_add_u64 v[198:199], s[84:85], 0, v[194:195]
	s_mov_b64 s[0:1], 0xb506000
	v_lshl_add_u64 v[198:199], v[198:199], 0, s[0:1]
	global_load_lds_dwordx4 v[198:199], off
.Ldk_skip1:
	s_cmp_ge_u32 s10, s30
	s_cbranch_scc1 .Ldk_skip2
	s_and_b32 s0, s5, 0x4000
	s_add_i32 m0, s28, s0
	v_lshl_add_u64 v[198:199], s[84:85], 0, v[194:195]
	s_mov_b64 s[0:1], 0xb508000
	v_lshl_add_u64 v[198:199], v[198:199], 0, s[0:1]
	global_load_lds_dwordx4 v[198:199], off
.Ldk_skip2:
	v_readlane_b32 s0, v252, 7
	s_cmpk_lt_u32 s0, 0x100
	s_cbranch_scc1 .Ldtop_skip
	s_cmp_eq_u32 s41, 2
	s_cselect_b64 s[6:7], -1, 0
	s_mov_b64 s[8:9], 0

.Ldtop_skip:
	v_lshl_add_u32 v196, s11, 13, v211
	s_add_i32 s0, s40, 0xffff8000
	s_and_b32 s0, s0, 0x8000
	v_add_u32_e32 v221, s0, v216
	v_add_u32_e32 v162, v196, v212
	v_add_u32_e32 v163, v196, v213
	v_add_u32_e32 v164, v196, v214
	v_add_u32_e32 v165, v196, v215
	v_add_u32_e32 v166, v221, v217
	v_add_u32_e32 v167, v221, v218
	v_add_u32_e32 v168, v221, v219
	v_add_u32_e32 v169, v221, v220
	ds_read_b128 v[130:133], v162
	ds_read_b128 v[134:137], v162 offset:4096
	ds_read_b128 v[138:141], v163
	ds_read_b128 v[142:145], v163 offset:4096
	ds_read_b128 v[222:225], v164
	ds_read_b128 v[226:229], v164 offset:4096
	ds_read_b128 v[230:233], v165
	ds_read_b128 v[234:237], v165 offset:4096
	ds_read_b128 v[238:241], v166 offset:32768
	ds_read_b128 v[242:245], v166 offset:36864
	ds_read_b128 v[246:249], v166 offset:40960
	ds_read_b128 v[180:183], v166 offset:45056
	s_waitcnt lgkmcnt(11)
	v_mfma_f32_32x32x16_bf16 v[98:113], v[130:133], v[146:149], v[66:81]
	ds_read_b128 v[130:133], v167 offset:32768
	s_waitcnt lgkmcnt(11)
	v_mfma_f32_32x32x16_bf16 v[82:97], v[134:137], v[146:149], v[66:81]
	ds_read_b128 v[134:137], v167 offset:36864
	s_waitcnt lgkmcnt(11)
	v_mfma_f32_32x32x16_bf16 v[98:113], v[138:141], v[150:153], v[98:113]
	ds_read_b128 v[138:141], v167 offset:40960
	s_waitcnt lgkmcnt(11)
	v_mfma_f32_32x32x16_bf16 v[82:97], v[142:145], v[150:153], v[82:97]
	ds_read_b128 v[142:145], v167 offset:45056
	s_waitcnt lgkmcnt(11)
	v_mfma_f32_32x32x16_bf16 v[98:113], v[222:225], v[154:157], v[98:113]
	ds_read_b128 v[222:225], v168 offset:32768
	s_waitcnt lgkmcnt(11)
	v_mfma_f32_32x32x16_bf16 v[82:97], v[226:229], v[154:157], v[82:97]
	ds_read_b128 v[226:229], v168 offset:36864
	s_waitcnt lgkmcnt(11)
	v_mfma_f32_32x32x16_bf16 v[98:113], v[230:233], v[158:161], v[98:113]
	ds_read_b128 v[230:233], v168 offset:40960
	s_waitcnt lgkmcnt(11)
	v_mfma_f32_32x32x16_bf16 v[82:97], v[234:237], v[158:161], v[82:97]
	ds_read_b128 v[234:237], v168 offset:45056
	s_waitcnt lgkmcnt(11)
	v_mfma_f32_32x32x16_bf16 v[2:17], v[238:241], v[114:117], v[2:17]
	ds_read_b128 v[238:241], v169 offset:32768
	s_waitcnt lgkmcnt(11)
	v_mfma_f32_32x32x16_bf16 v[50:65], v[242:245], v[114:117], v[50:65]
	ds_read_b128 v[242:245], v169 offset:36864
	s_waitcnt lgkmcnt(11)
	v_mfma_f32_32x32x16_bf16 v[34:49], v[246:249], v[114:117], v[34:49]
	ds_read_b128 v[246:249], v169 offset:40960
	s_waitcnt lgkmcnt(11)
	v_mfma_f32_32x32x16_bf16 v[18:33], v[180:183], v[114:117], v[18:33]
	ds_read_b128 v[180:183], v169 offset:45056
	s_waitcnt lgkmcnt(11)
	v_mfma_f32_32x32x16_bf16 v[2:17], v[130:133], v[118:121], v[2:17]
	s_waitcnt lgkmcnt(10)
	v_mfma_f32_32x32x16_bf16 v[50:65], v[134:137], v[118:121], v[50:65]
	s_waitcnt lgkmcnt(9)
	v_mfma_f32_32x32x16_bf16 v[34:49], v[138:141], v[118:121], v[34:49]
	s_waitcnt lgkmcnt(8)
	v_mfma_f32_32x32x16_bf16 v[18:33], v[142:145], v[118:121], v[18:33]
	s_waitcnt lgkmcnt(7)
	v_mfma_f32_32x32x16_bf16 v[2:17], v[222:225], v[122:125], v[2:17]
	s_waitcnt lgkmcnt(6)
	v_mfma_f32_32x32x16_bf16 v[50:65], v[226:229], v[122:125], v[50:65]
	s_waitcnt lgkmcnt(5)
	v_mfma_f32_32x32x16_bf16 v[34:49], v[230:233], v[122:125], v[34:49]
	s_waitcnt lgkmcnt(4)
	v_mfma_f32_32x32x16_bf16 v[18:33], v[234:237], v[122:125], v[18:33]
	s_waitcnt lgkmcnt(3)
	v_mfma_f32_32x32x16_bf16 v[2:17], v[238:241], v[126:129], v[2:17]
	s_waitcnt lgkmcnt(2)
	v_mfma_f32_32x32x16_bf16 v[50:65], v[242:245], v[126:129], v[50:65]
	s_waitcnt lgkmcnt(1)
	v_mfma_f32_32x32x16_bf16 v[34:49], v[246:249], v[126:129], v[34:49]
	s_waitcnt lgkmcnt(0)
	v_mfma_f32_32x32x16_bf16 v[18:33], v[180:183], v[126:129], v[18:33]
	s_mov_b64 s[6:7], 0
	s_mov_b64 s[8:9], 0

.Ldv_mid_fast:
	v_cvt_pk_bf16_f32 v114, v130, v131
	v_cvt_pk_bf16_f32 v115, v132, v133
	v_cvt_pk_bf16_f32 v116, v134, v135
	v_cvt_pk_bf16_f32 v117, v136, v137
	v_cvt_pk_bf16_f32 v118, v138, v139
	v_cvt_pk_bf16_f32 v119, v140, v141
	v_cvt_pk_bf16_f32 v120, v142, v143
	v_cvt_pk_bf16_f32 v121, v144, v145
	v_cvt_pk_bf16_f32 v122, v222, v223
	v_cvt_pk_bf16_f32 v123, v224, v225
	v_cvt_pk_bf16_f32 v124, v226, v227
	v_cvt_pk_bf16_f32 v125, v228, v229
	v_cvt_pk_bf16_f32 v126, v230, v231
	v_cvt_pk_bf16_f32 v127, v232, v233
	v_cvt_pk_bf16_f32 v128, v234, v235
	v_cvt_pk_bf16_f32 v129, v236, v237
	v_add_f32_e32 v197, v197, v199
	s_addk_i32 s5, 0x4000
	s_cmp_ge_u32 s41, s30
	s_cbranch_scc1 .Ldv_skip1
	s_and_b32 s0, s40, 0x8000
	s_add_i32 s0, s28, s0
	v_lshl_add_u64 v[198:199], s[84:85], 0, v[192:193]
	s_add_i32 m0, s0, 0x8000
	v_lshl_add_u64 v[198:199], v[198:199], 0, s[78:79]
	global_load_lds_dwordx4 v[198:199], off
	s_add_i32 m0, s0, 0xa000
	v_lshl_add_u64 v[198:199], s[84:85], 0, v[190:191]
	v_lshl_add_u64 v[198:199], v[198:199], 0, s[78:79]
	global_load_lds_dwordx4 v[198:199], off
.Ldv_skip1:
	s_add_i32 s0, s41, 1
	s_cmp_ge_u32 s0, s30
	s_cbranch_scc1 .Ldv_skip2
	s_add_i32 s0, s40, 0x4000
	s_and_b32 s0, s0, 0xc000
	s_add_i32 s0, s28, s0
	v_lshl_add_u64 v[198:199], s[84:85], 0, v[192:193]
	s_add_i32 m0, s0, 0x8000
	v_lshl_add_u64 v[198:199], v[198:199], 0, s[80:81]
	global_load_lds_dwordx4 v[198:199], off
	s_add_i32 m0, s0, 0xa000
	v_lshl_add_u64 v[198:199], s[84:85], 0, v[190:191]
	v_lshl_add_u64 v[198:199], v[198:199], 0, s[80:81]
	global_load_lds_dwordx4 v[198:199], off
.Ldv_skip2:
	s_and_b32 s0, s5, 0x4000
	v_add_u32_e32 v196, s0, v211
	v_lshl_add_u32 v221, s11, 14, v216
	v_add_u32_e32 v162, v196, v212
	v_add_u32_e32 v163, v196, v213
	v_add_u32_e32 v164, v196, v214
	v_add_u32_e32 v165, v196, v215
	v_add_u32_e32 v166, v221, v217
	v_add_u32_e32 v167, v221, v218
	v_add_u32_e32 v168, v221, v219
	v_add_u32_e32 v169, v221, v220
	ds_read_b128 v[130:133], v162
	ds_read_b128 v[134:137], v162 offset:4096
	ds_read_b128 v[138:141], v163
	ds_read_b128 v[142:145], v163 offset:4096
	ds_read_b128 v[222:225], v164
	ds_read_b128 v[226:229], v164 offset:4096
	ds_read_b128 v[230:233], v165
	ds_read_b128 v[234:237], v165 offset:4096
	ds_read_b128 v[238:241], v166 offset:32768
	ds_read_b128 v[242:245], v166 offset:36864
	ds_read_b128 v[246:249], v166 offset:40960
	ds_read_b128 v[180:183], v166 offset:45056
	s_waitcnt lgkmcnt(11)
	v_mfma_f32_32x32x16_bf16 v[98:113], v[130:133], v[146:149], v[66:81]
	ds_read_b128 v[130:133], v167 offset:32768
	s_waitcnt lgkmcnt(11)
	v_mfma_f32_32x32x16_bf16 v[82:97], v[134:137], v[146:149], v[66:81]
	ds_read_b128 v[134:137], v167 offset:36864
	s_waitcnt lgkmcnt(11)
	v_mfma_f32_32x32x16_bf16 v[98:113], v[138:141], v[150:153], v[98:113]
	ds_read_b128 v[138:141], v167 offset:40960
	s_waitcnt lgkmcnt(11)
	v_mfma_f32_32x32x16_bf16 v[82:97], v[142:145], v[150:153], v[82:97]
	ds_read_b128 v[142:145], v167 offset:45056
	s_waitcnt lgkmcnt(11)
	v_mfma_f32_32x32x16_bf16 v[98:113], v[222:225], v[154:157], v[98:113]
	ds_read_b128 v[222:225], v168 offset:32768
	s_waitcnt lgkmcnt(11)
	v_mfma_f32_32x32x16_bf16 v[82:97], v[226:229], v[154:157], v[82:97]
	ds_read_b128 v[226:229], v168 offset:36864
	s_waitcnt lgkmcnt(11)
	v_mfma_f32_32x32x16_bf16 v[98:113], v[230:233], v[158:161], v[98:113]
	ds_read_b128 v[230:233], v168 offset:40960
	s_waitcnt lgkmcnt(11)
	v_mfma_f32_32x32x16_bf16 v[82:97], v[234:237], v[158:161], v[82:97]
	ds_read_b128 v[234:237], v168 offset:45056
	s_waitcnt lgkmcnt(11)
	v_mfma_f32_32x32x16_bf16 v[2:17], v[238:241], v[114:117], v[2:17]
	ds_read_b128 v[238:241], v169 offset:32768
	s_waitcnt lgkmcnt(11)
	v_mfma_f32_32x32x16_bf16 v[50:65], v[242:245], v[114:117], v[50:65]
	ds_read_b128 v[242:245], v169 offset:36864
	s_waitcnt lgkmcnt(11)
	v_mfma_f32_32x32x16_bf16 v[34:49], v[246:249], v[114:117], v[34:49]
	ds_read_b128 v[246:249], v169 offset:40960
	s_waitcnt lgkmcnt(11)
	v_mfma_f32_32x32x16_bf16 v[18:33], v[180:183], v[114:117], v[18:33]
	ds_read_b128 v[180:183], v169 offset:45056
	s_waitcnt lgkmcnt(11)
	v_mfma_f32_32x32x16_bf16 v[2:17], v[130:133], v[118:121], v[2:17]
	s_waitcnt lgkmcnt(10)
	v_mfma_f32_32x32x16_bf16 v[50:65], v[134:137], v[118:121], v[50:65]
	s_waitcnt lgkmcnt(9)
	v_mfma_f32_32x32x16_bf16 v[34:49], v[138:141], v[118:121], v[34:49]
	s_waitcnt lgkmcnt(8)
	v_mfma_f32_32x32x16_bf16 v[18:33], v[142:145], v[118:121], v[18:33]
	s_waitcnt lgkmcnt(7)
	v_mfma_f32_32x32x16_bf16 v[2:17], v[222:225], v[122:125], v[2:17]
	s_waitcnt lgkmcnt(6)
	v_mfma_f32_32x32x16_bf16 v[50:65], v[226:229], v[122:125], v[50:65]
	s_waitcnt lgkmcnt(5)
	v_mfma_f32_32x32x16_bf16 v[34:49], v[230:233], v[122:125], v[34:49]
	s_waitcnt lgkmcnt(4)
	v_mfma_f32_32x32x16_bf16 v[18:33], v[234:237], v[122:125], v[18:33]
	s_waitcnt lgkmcnt(3)
	v_mfma_f32_32x32x16_bf16 v[2:17], v[238:241], v[126:129], v[2:17]
	s_waitcnt lgkmcnt(2)
	v_mfma_f32_32x32x16_bf16 v[50:65], v[242:245], v[126:129], v[50:65]
	s_waitcnt lgkmcnt(1)
	v_mfma_f32_32x32x16_bf16 v[34:49], v[246:249], v[126:129], v[34:49]
	s_waitcnt lgkmcnt(0)
	v_mfma_f32_32x32x16_bf16 v[18:33], v[180:183], v[126:129], v[18:33]
	s_cmp_ge_u32 s41, s30
	s_cbranch_scc1 .Ldend_skip
	v_readlane_b32 s0, v252, 7
	s_cmpk_lt_u32 s0, 0x100
	s_cbranch_scc0 .Ldend_skip
	s_mov_b64 s[6:7], 0
	s_mov_b64 s[8:9], 0

.Ldend_skip:
	s_waitcnt vmcnt(0)
	s_barrier
